# P0 filter-MLP weight staging loads batched (was load-wait-store per pair)
# speedup vs baseline: 1.0421x; 1.0058x over previous
.LBB0_66:
	v_ashrrev_i32_e32 v11, 31, v7
	v_mov_b32_e32 v10, v7
	v_ashrrev_i32_e32 v35, 31, v6
	v_mov_b32_e32 v34, v6
	s_waitcnt lgkmcnt(0)
	v_lshl_add_u64 v[34:35], v[34:35], 2, s[74:75]
	v_lshl_add_u64 v[10:11], v[10:11], 2, s[74:75]
	global_load_dword v100, v[34:35], off
	s_nop 0
	global_load_dword v101, v[10:11], off
	v_add_u32_e32 v34, 0x200, v7
	v_ashrrev_i32_e32 v35, 31, v34
	v_lshl_add_u64 v[34:35], v[34:35], 2, s[74:75]
	v_add_u32_e32 v2, -8, v2
	s_add_i32 s38, s38, 16
	v_cmp_eq_u32_e32 vcc, 0, v2
	s_or_b64 s[36:37], vcc, s[36:37]
	v_add_u32_e32 v10, 0x200, v6
	v_ashrrev_i32_e32 v11, 31, v10
	v_lshl_add_u64 v[10:11], v[10:11], 2, s[74:75]
	global_load_dword v102, v[10:11], off
	s_nop 0
	global_load_dword v103, v[34:35], off
	v_add_u32_e32 v34, 0x400, v7
	v_ashrrev_i32_e32 v35, 31, v34
	v_lshl_add_u64 v[34:35], v[34:35], 2, s[74:75]
	v_add_u32_e32 v10, 0x400, v6
	v_ashrrev_i32_e32 v11, 31, v10
	v_lshl_add_u64 v[10:11], v[10:11], 2, s[74:75]
	global_load_dword v104, v[10:11], off
	s_nop 0
	global_load_dword v105, v[34:35], off
	v_add_u32_e32 v34, 0x600, v7
	v_ashrrev_i32_e32 v35, 31, v34
	v_lshl_add_u64 v[34:35], v[34:35], 2, s[74:75]
	v_add_u32_e32 v10, 0x600, v6
	v_ashrrev_i32_e32 v11, 31, v10
	v_lshl_add_u64 v[10:11], v[10:11], 2, s[74:75]
	global_load_dword v106, v[10:11], off
	s_nop 0
	global_load_dword v107, v[34:35], off
	v_add_u32_e32 v34, 0x800, v7
	v_ashrrev_i32_e32 v35, 31, v34
	v_lshl_add_u64 v[34:35], v[34:35], 2, s[74:75]
	v_add_u32_e32 v10, 0x800, v6
	v_ashrrev_i32_e32 v11, 31, v10
	v_lshl_add_u64 v[10:11], v[10:11], 2, s[74:75]
	global_load_dword v108, v[10:11], off
	s_nop 0
	global_load_dword v109, v[34:35], off
	v_add_u32_e32 v34, 0xa00, v7
	v_ashrrev_i32_e32 v35, 31, v34
	v_lshl_add_u64 v[34:35], v[34:35], 2, s[74:75]
	v_add_u32_e32 v10, 0xa00, v6
	v_ashrrev_i32_e32 v11, 31, v10
	v_lshl_add_u64 v[10:11], v[10:11], 2, s[74:75]
	global_load_dword v110, v[10:11], off
	s_nop 0
	global_load_dword v111, v[34:35], off
	v_add_u32_e32 v34, 0xc00, v7
	v_ashrrev_i32_e32 v35, 31, v34
	v_lshl_add_u64 v[34:35], v[34:35], 2, s[74:75]
	v_add_u32_e32 v10, 0xc00, v6
	v_ashrrev_i32_e32 v11, 31, v10
	v_lshl_add_u64 v[10:11], v[10:11], 2, s[74:75]
	global_load_dword v112, v[10:11], off
	s_nop 0
	global_load_dword v113, v[34:35], off
	v_add_u32_e32 v34, 0xe00, v7
	v_ashrrev_i32_e32 v35, 31, v34
	v_lshl_add_u64 v[34:35], v[34:35], 2, s[74:75]
	v_add_u32_e32 v7, 0x1000, v7
	v_add_u32_e32 v10, 0xe00, v6
	v_ashrrev_i32_e32 v11, 31, v10
	v_lshl_add_u64 v[10:11], v[10:11], 2, s[74:75]
	global_load_dword v114, v[10:11], off
	s_nop 0
	global_load_dword v115, v[34:35], off
	v_add_u32_e32 v6, 0x1000, v6
	s_waitcnt vmcnt(0)
	ds_write2st64_b32 v8, v100, v101 offset1:4
	ds_write2st64_b32 v8, v102, v103 offset0:8 offset1:12
	ds_write2st64_b32 v8, v104, v105 offset0:16 offset1:20
	ds_write2st64_b32 v8, v106, v107 offset0:24 offset1:28
	ds_write2st64_b32 v8, v108, v109 offset0:32 offset1:36
	ds_write2st64_b32 v8, v110, v111 offset0:40 offset1:44
	ds_write2st64_b32 v8, v112, v113 offset0:48 offset1:52
	ds_write2st64_b32 v8, v114, v115 offset0:56 offset1:60
	v_add_u32_e32 v8, 0x4000, v8
	v_mov_b32_e32 v9, s38
	s_andn2_b64 exec, exec, s[36:37]
	s_cbranch_execnz .LBB0_66
	s_or_b64 exec, exec, s[36:37]

.LBB0_99:
	v_ashrrev_i32_e32 v35, 31, v7
	v_mov_b32_e32 v34, v7
	v_ashrrev_i32_e32 v37, 31, v6
	v_mov_b32_e32 v36, v6
	s_waitcnt lgkmcnt(0)
	v_lshl_add_u64 v[36:37], v[36:37], 2, s[78:79]
	v_lshl_add_u64 v[34:35], v[34:35], 2, s[78:79]
	global_load_dword v100, v[36:37], off
	s_nop 0
	global_load_dword v101, v[34:35], off
	v_add_u32_e32 v36, 0x200, v7
	v_ashrrev_i32_e32 v37, 31, v36
	v_lshl_add_u64 v[36:37], v[36:37], 2, s[78:79]
	v_add_u32_e32 v2, -8, v2
	s_add_i32 s38, s38, 16
	v_cmp_eq_u32_e32 vcc, 0, v2
	s_or_b64 s[36:37], vcc, s[36:37]
	v_add_u32_e32 v34, 0x200, v6
	v_ashrrev_i32_e32 v35, 31, v34
	v_lshl_add_u64 v[34:35], v[34:35], 2, s[78:79]
	global_load_dword v102, v[34:35], off
	s_nop 0
	global_load_dword v103, v[36:37], off
	v_add_u32_e32 v36, 0x400, v7
	v_ashrrev_i32_e32 v37, 31, v36
	v_lshl_add_u64 v[36:37], v[36:37], 2, s[78:79]
	v_add_u32_e32 v34, 0x400, v6
	v_ashrrev_i32_e32 v35, 31, v34
	v_lshl_add_u64 v[34:35], v[34:35], 2, s[78:79]
	global_load_dword v104, v[34:35], off
	s_nop 0
	global_load_dword v105, v[36:37], off
	v_add_u32_e32 v36, 0x600, v7
	v_ashrrev_i32_e32 v37, 31, v36
	v_lshl_add_u64 v[36:37], v[36:37], 2, s[78:79]
	v_add_u32_e32 v34, 0x600, v6
	v_ashrrev_i32_e32 v35, 31, v34
	v_lshl_add_u64 v[34:35], v[34:35], 2, s[78:79]
	global_load_dword v106, v[34:35], off
	s_nop 0
	global_load_dword v107, v[36:37], off
	v_add_u32_e32 v36, 0x800, v7
	v_ashrrev_i32_e32 v37, 31, v36
	v_lshl_add_u64 v[36:37], v[36:37], 2, s[78:79]
	v_add_u32_e32 v34, 0x800, v6
	v_ashrrev_i32_e32 v35, 31, v34
	v_lshl_add_u64 v[34:35], v[34:35], 2, s[78:79]
	global_load_dword v108, v[34:35], off
	s_nop 0
	global_load_dword v109, v[36:37], off
	v_add_u32_e32 v36, 0xa00, v7
	v_ashrrev_i32_e32 v37, 31, v36
	v_lshl_add_u64 v[36:37], v[36:37], 2, s[78:79]
	v_add_u32_e32 v34, 0xa00, v6
	v_ashrrev_i32_e32 v35, 31, v34
	v_lshl_add_u64 v[34:35], v[34:35], 2, s[78:79]
	global_load_dword v110, v[34:35], off
	s_nop 0
	global_load_dword v111, v[36:37], off
	v_add_u32_e32 v36, 0xc00, v7
	v_ashrrev_i32_e32 v37, 31, v36
	v_lshl_add_u64 v[36:37], v[36:37], 2, s[78:79]
	v_add_u32_e32 v34, 0xc00, v6
	v_ashrrev_i32_e32 v35, 31, v34
	v_lshl_add_u64 v[34:35], v[34:35], 2, s[78:79]
	global_load_dword v112, v[34:35], off
	s_nop 0
	global_load_dword v113, v[36:37], off
	v_add_u32_e32 v36, 0xe00, v7
	v_ashrrev_i32_e32 v37, 31, v36
	v_lshl_add_u64 v[36:37], v[36:37], 2, s[78:79]
	v_add_u32_e32 v7, 0x1000, v7
	v_add_u32_e32 v34, 0xe00, v6
	v_ashrrev_i32_e32 v35, 31, v34
	v_lshl_add_u64 v[34:35], v[34:35], 2, s[78:79]
	global_load_dword v114, v[34:35], off
	s_nop 0
	global_load_dword v115, v[36:37], off
	v_add_u32_e32 v6, 0x1000, v6
	s_waitcnt vmcnt(0)
	ds_write2st64_b32 v8, v100, v101 offset1:4
	ds_write2st64_b32 v8, v102, v103 offset0:8 offset1:12
	ds_write2st64_b32 v8, v104, v105 offset0:16 offset1:20
	ds_write2st64_b32 v8, v106, v107 offset0:24 offset1:28
	ds_write2st64_b32 v8, v108, v109 offset0:32 offset1:36
	ds_write2st64_b32 v8, v110, v111 offset0:40 offset1:44
	ds_write2st64_b32 v8, v112, v113 offset0:48 offset1:52
	ds_write2st64_b32 v8, v114, v115 offset0:56 offset1:60
	v_add_u32_e32 v8, 0x4000, v8
	v_mov_b32_e32 v9, s38
	s_andn2_b64 exec, exec, s[36:37]
	s_cbranch_execnz .LBB0_99
	s_or_b64 exec, exec, s[36:37]

.LBB0_132:
	v_ashrrev_i32_e32 v37, 31, v6
	v_mov_b32_e32 v36, v6
	v_ashrrev_i32_e32 v35, 31, v7
	v_mov_b32_e32 v34, v7
	s_waitcnt lgkmcnt(0)
	v_lshl_add_u64 v[36:37], v[36:37], 2, s[82:83]
	v_lshl_add_u64 v[34:35], v[34:35], 2, s[82:83]
	global_load_dword v100, v[36:37], off
	global_load_dword v101, v[34:35], off
	v_add_u32_e32 v34, 0x200, v6
	v_add_u32_e32 v36, 0x200, v7
	v_ashrrev_i32_e32 v35, 31, v34
	v_ashrrev_i32_e32 v37, 31, v36
	v_lshl_add_u64 v[34:35], v[34:35], 2, s[82:83]
	v_lshl_add_u64 v[36:37], v[36:37], 2, s[82:83]
	v_add_u32_e32 v2, -8, v2
	s_add_i32 s38, s38, 16
	v_cmp_eq_u32_e32 vcc, 0, v2
	s_or_b64 s[36:37], vcc, s[36:37]
	global_load_dword v102, v[34:35], off
	global_load_dword v103, v[36:37], off
	v_add_u32_e32 v34, 0x400, v6
	v_add_u32_e32 v36, 0x400, v7
	v_ashrrev_i32_e32 v35, 31, v34
	v_ashrrev_i32_e32 v37, 31, v36
	v_lshl_add_u64 v[34:35], v[34:35], 2, s[82:83]
	v_lshl_add_u64 v[36:37], v[36:37], 2, s[82:83]
	global_load_dword v104, v[34:35], off
	global_load_dword v105, v[36:37], off
	v_add_u32_e32 v34, 0x600, v6
	v_add_u32_e32 v36, 0x600, v7
	v_ashrrev_i32_e32 v35, 31, v34
	v_ashrrev_i32_e32 v37, 31, v36
	v_lshl_add_u64 v[34:35], v[34:35], 2, s[82:83]
	v_lshl_add_u64 v[36:37], v[36:37], 2, s[82:83]
	global_load_dword v106, v[34:35], off
	global_load_dword v107, v[36:37], off
	v_add_u32_e32 v34, 0x800, v6
	v_add_u32_e32 v36, 0x800, v7
	v_ashrrev_i32_e32 v35, 31, v34
	v_ashrrev_i32_e32 v37, 31, v36
	v_lshl_add_u64 v[34:35], v[34:35], 2, s[82:83]
	v_lshl_add_u64 v[36:37], v[36:37], 2, s[82:83]
	global_load_dword v108, v[34:35], off
	global_load_dword v109, v[36:37], off
	v_add_u32_e32 v34, 0xa00, v6
	v_add_u32_e32 v36, 0xa00, v7
	v_ashrrev_i32_e32 v35, 31, v34
	v_ashrrev_i32_e32 v37, 31, v36
	v_lshl_add_u64 v[34:35], v[34:35], 2, s[82:83]
	v_lshl_add_u64 v[36:37], v[36:37], 2, s[82:83]
	global_load_dword v110, v[34:35], off
	global_load_dword v111, v[36:37], off
	v_add_u32_e32 v34, 0xc00, v6
	v_add_u32_e32 v36, 0xc00, v7
	v_ashrrev_i32_e32 v35, 31, v34
	v_ashrrev_i32_e32 v37, 31, v36
	v_lshl_add_u64 v[34:35], v[34:35], 2, s[82:83]
	v_lshl_add_u64 v[36:37], v[36:37], 2, s[82:83]
	global_load_dword v112, v[34:35], off
	global_load_dword v113, v[36:37], off
	v_add_u32_e32 v34, 0xe00, v6
	v_add_u32_e32 v36, 0xe00, v7
	v_ashrrev_i32_e32 v35, 31, v34
	v_ashrrev_i32_e32 v37, 31, v36
	v_lshl_add_u64 v[34:35], v[34:35], 2, s[82:83]
	v_lshl_add_u64 v[36:37], v[36:37], 2, s[82:83]
	v_add_u32_e32 v7, 0x1000, v7
	v_add_u32_e32 v6, 0x1000, v6
	global_load_dword v114, v[34:35], off
	global_load_dword v115, v[36:37], off
	s_waitcnt vmcnt(0)
	ds_write2st64_b32 v8, v100, v101 offset1:4
	ds_write2st64_b32 v8, v102, v103 offset0:8 offset1:12
	ds_write2st64_b32 v8, v104, v105 offset0:16 offset1:20
	ds_write2st64_b32 v8, v106, v107 offset0:24 offset1:28
	ds_write2st64_b32 v8, v108, v109 offset0:32 offset1:36
	ds_write2st64_b32 v8, v110, v111 offset0:40 offset1:44
	ds_write2st64_b32 v8, v112, v113 offset0:48 offset1:52
	ds_write2st64_b32 v8, v114, v115 offset0:56 offset1:60
	v_add_u32_e32 v8, 0x4000, v8
	v_mov_b32_e32 v9, s38
	s_andn2_b64 exec, exec, s[36:37]
	s_cbranch_execnz .LBB0_132
	s_or_b64 exec, exec, s[36:37]
